# P3 swap + EpiRes prefetch + static prio 1 for waves 0-3 in differential attention
# baseline (speedup 1.0000x reference)
.LBB0_548:
	s_or_b64 exec, exec, s[4:5]
	s_cmpk_gt_i32 s3, 0xff
	s_waitcnt lgkmcnt(0)
	s_barrier
	s_cbranch_scc1 .LBB0_582
	v_readfirstlane_b32 s86, v225
	s_lshr_b32 s86, s86, 8
	s_cmp_ge_u32 s86, 1
	s_cbranch_scc1 .Ldf_prio_done
	s_setprio 1
.Ldf_prio_done:
	v_mov_b32_e32 v213, 0
	global_load_dword v227, v213, s[52:53]
	v_mbcnt_lo_u32_b32 v0, -1, 0
	s_mov_b32 s5, 0
	s_movk_i32 s44, 0x3000
	v_mov_b64_e32 v[214:215], s[12:13]
	s_mov_b64 s[6:7], 0x1800
	s_movk_i32 s45, 0x1000
	s_movk_i32 s46, 0x110
	s_movk_i32 s47, 0x2000
	s_movk_i32 s48, 0x90
	s_mov_b32 s49, 0xf149f2ca
	s_mov_b32 s50, 0x41000000
	v_mbcnt_hi_u32_b32 v228, -1, v0
	s_mov_b32 s51, 0x800000
	s_movk_i32 s52, 0x4000
	s_mov_b32 s53, 0x8000
	s_mov_b32 s54, 0xc000
	s_mov_b32 s55, 0x10000
	s_mov_b32 s56, 0x14000
	s_mov_b32 s57, 0x18000
	v_mov_b32_e32 v229, 0xf149f2ca
	s_mov_b32 s58, s3
	s_branch .LBB0_551

.LBB0_582:
	s_setprio 0
	s_cmpk_gt_i32 s3, 0x1ff
	s_cbranch_scc1 .LBB0_601
	v_mbcnt_lo_u32_b32 v0, -1, 0
	s_movk_i32 s44, 0x3000
	s_waitcnt vmcnt(3)
	v_mov_b64_e32 v[146:147], s[12:13]
	s_mov_b32 s9, 0
	v_mov_b32_e32 v1, 0
	s_mov_b32 s45, 0xc000
	s_movk_i32 s46, 0x2000
	s_movk_i32 s47, 0x110
	s_movk_i32 s48, 0x90
	s_mov_b32 s49, 0x43180000
	s_movk_i32 s50, 0x1000
	s_mov_b32 s51, 0xd000
	s_mov_b32 s52, 0x19000
	s_mov_b32 s53, 0x25000
	s_mov_b32 s54, 0x31000
	s_mov_b32 s55, 0x3d000
	s_mov_b32 s56, 0x49000
	s_mov_b32 s57, 0x55000
	s_movk_i32 s58, 0x4000
	s_mov_b32 s59, 0x8000
	s_mov_b32 s60, 0x10000
	s_mov_b32 s61, 0x14000
	s_mov_b32 s62, 0x18000
	v_mov_b32_e32 v194, 0xf149f2ca
	v_mbcnt_hi_u32_b32 v195, -1, v0
	v_mov_b32_e32 v196, 0x3000
	s_mov_b32 s63, s3
	s_branch .LBB0_585
